# top-16 block selection: replace 64x64 readlane rank loop by 32-step scalar bisection on order-preserving keys (ballot+popcount), exact same selection incl. index tie-break
# speedup vs baseline: 1.3680x; 1.0213x over previous
; __device__ __forceinline__ void nsa_unit(int b, int qt, const bf16_t* proj, const bf16_t* vt, const bf16_t* kc, const bf16_t* vcT, bf16_t* ab0, LAS unsigned char* lds, int tid, int wid, int lane) {
;     ...
;     for (int i = 0; i < 8; ++i) {
;       const int qi = wid * 8 + i;
;       const bool valid = lane <= qt, forced = (lane == 0) || (lane == qt) || (lane == qt - 1);
;       float val = ((imp0[qi * 65 + lane] * linvL[qi] + imp1[qi * 65 + lane] * linvL[64 + qi]) + imp2[qi * 65 + lane] * linvL[128 + qi]) + imp3[qi * 65 + lane] * linvL[192 + qi];
;       val = valid ? (forced ? val + 1.0e4f : val) : -1.0e30f;
;       int rank = 0;
; #pragma unroll 4
;       for (int jj = 0; jj < 64; ++jj) {
;         const float o = __builtin_bit_cast(float, __builtin_amdgcn_readlane(__builtin_bit_cast(int, val), jj));
;         rank += (o > val || (o == val && jj < lane)) ? 1 : 0;
;       }
;       const unsigned long long mk = __ballot(rank < 16);
;       if (lane == 0) { selw[qi * 2] = (unsigned)mk; selw[qi * 2 + 1] = (unsigned)(mk >> 32); }
;     }
.LBB0_689:
	s_or_b64 exec, exec, s[14:15]
	v_xor_b32_e32 v35, 0x80000000, v0
	s_mov_b32 s97, 0
	s_or_b32 s98, s97, 0x80000000
	v_cmp_le_u32_e64 s[14:15], s98, v35
	s_bcnt1_i32_b64 s100, s[14:15]
	s_cmp_ge_u32 s100, 16
	s_cselect_b32 s97, s98, s97
	s_or_b32 s98, s97, 0x40000000
	v_cmp_le_u32_e64 s[14:15], s98, v35
	s_bcnt1_i32_b64 s100, s[14:15]
	s_cmp_ge_u32 s100, 16
	s_cselect_b32 s97, s98, s97
	s_or_b32 s98, s97, 0x20000000
	v_cmp_le_u32_e64 s[14:15], s98, v35
	s_bcnt1_i32_b64 s100, s[14:15]
	s_cmp_ge_u32 s100, 16
	s_cselect_b32 s97, s98, s97
	s_or_b32 s98, s97, 0x10000000
	v_cmp_le_u32_e64 s[14:15], s98, v35
	s_bcnt1_i32_b64 s100, s[14:15]
	s_cmp_ge_u32 s100, 16
	s_cselect_b32 s97, s98, s97
	s_or_b32 s98, s97, 0x8000000
	v_cmp_le_u32_e64 s[14:15], s98, v35
	s_bcnt1_i32_b64 s100, s[14:15]
	s_cmp_ge_u32 s100, 16
	s_cselect_b32 s97, s98, s97
	s_or_b32 s98, s97, 0x4000000
	v_cmp_le_u32_e64 s[14:15], s98, v35
	s_bcnt1_i32_b64 s100, s[14:15]
	s_cmp_ge_u32 s100, 16
	s_cselect_b32 s97, s98, s97
	s_or_b32 s98, s97, 0x2000000
	v_cmp_le_u32_e64 s[14:15], s98, v35
	s_bcnt1_i32_b64 s100, s[14:15]
	s_cmp_ge_u32 s100, 16
	s_cselect_b32 s97, s98, s97
	s_or_b32 s98, s97, 0x1000000
	v_cmp_le_u32_e64 s[14:15], s98, v35
	s_bcnt1_i32_b64 s100, s[14:15]
	s_cmp_ge_u32 s100, 16
	s_cselect_b32 s97, s98, s97
	s_or_b32 s98, s97, 0x800000
	v_cmp_le_u32_e64 s[14:15], s98, v35
	s_bcnt1_i32_b64 s100, s[14:15]
	s_cmp_ge_u32 s100, 16
	s_cselect_b32 s97, s98, s97
	s_or_b32 s98, s97, 0x400000
	v_cmp_le_u32_e64 s[14:15], s98, v35
	s_bcnt1_i32_b64 s100, s[14:15]
	s_cmp_ge_u32 s100, 16
	s_cselect_b32 s97, s98, s97
	s_or_b32 s98, s97, 0x200000
	v_cmp_le_u32_e64 s[14:15], s98, v35
	s_bcnt1_i32_b64 s100, s[14:15]
	s_cmp_ge_u32 s100, 16
	s_cselect_b32 s97, s98, s97
	s_or_b32 s98, s97, 0x100000
	v_cmp_le_u32_e64 s[14:15], s98, v35
	s_bcnt1_i32_b64 s100, s[14:15]
	s_cmp_ge_u32 s100, 16
	s_cselect_b32 s97, s98, s97
	s_or_b32 s98, s97, 0x80000
	v_cmp_le_u32_e64 s[14:15], s98, v35
	s_bcnt1_i32_b64 s100, s[14:15]
	s_cmp_ge_u32 s100, 16
	s_cselect_b32 s97, s98, s97
	s_or_b32 s98, s97, 0x40000
	v_cmp_le_u32_e64 s[14:15], s98, v35
	s_bcnt1_i32_b64 s100, s[14:15]
	s_cmp_ge_u32 s100, 16
	s_cselect_b32 s97, s98, s97
	s_or_b32 s98, s97, 0x20000
	v_cmp_le_u32_e64 s[14:15], s98, v35
	s_bcnt1_i32_b64 s100, s[14:15]
	s_cmp_ge_u32 s100, 16
	s_cselect_b32 s97, s98, s97
	s_or_b32 s98, s97, 0x10000
	v_cmp_le_u32_e64 s[14:15], s98, v35
	s_bcnt1_i32_b64 s100, s[14:15]
	s_cmp_ge_u32 s100, 16
	s_cselect_b32 s97, s98, s97
	s_or_b32 s98, s97, 0x8000
	v_cmp_le_u32_e64 s[14:15], s98, v35
	s_bcnt1_i32_b64 s100, s[14:15]
	s_cmp_ge_u32 s100, 16
	s_cselect_b32 s97, s98, s97
	s_or_b32 s98, s97, 0x4000
	v_cmp_le_u32_e64 s[14:15], s98, v35
	s_bcnt1_i32_b64 s100, s[14:15]
	s_cmp_ge_u32 s100, 16
	s_cselect_b32 s97, s98, s97
	s_or_b32 s98, s97, 0x2000
	v_cmp_le_u32_e64 s[14:15], s98, v35
	s_bcnt1_i32_b64 s100, s[14:15]
	s_cmp_ge_u32 s100, 16
	s_cselect_b32 s97, s98, s97
	s_or_b32 s98, s97, 0x1000
	v_cmp_le_u32_e64 s[14:15], s98, v35
	s_bcnt1_i32_b64 s100, s[14:15]
	s_cmp_ge_u32 s100, 16
	s_cselect_b32 s97, s98, s97
	s_or_b32 s98, s97, 0x800
	v_cmp_le_u32_e64 s[14:15], s98, v35
	s_bcnt1_i32_b64 s100, s[14:15]
	s_cmp_ge_u32 s100, 16
	s_cselect_b32 s97, s98, s97
	s_or_b32 s98, s97, 0x400
	v_cmp_le_u32_e64 s[14:15], s98, v35
	s_bcnt1_i32_b64 s100, s[14:15]
	s_cmp_ge_u32 s100, 16
	s_cselect_b32 s97, s98, s97
	s_or_b32 s98, s97, 0x200
	v_cmp_le_u32_e64 s[14:15], s98, v35
	s_bcnt1_i32_b64 s100, s[14:15]
	s_cmp_ge_u32 s100, 16
	s_cselect_b32 s97, s98, s97
	s_or_b32 s98, s97, 0x100
	v_cmp_le_u32_e64 s[14:15], s98, v35
	s_bcnt1_i32_b64 s100, s[14:15]
	s_cmp_ge_u32 s100, 16
	s_cselect_b32 s97, s98, s97
	s_or_b32 s98, s97, 0x80
	v_cmp_le_u32_e64 s[14:15], s98, v35
	s_bcnt1_i32_b64 s100, s[14:15]
	s_cmp_ge_u32 s100, 16
	s_cselect_b32 s97, s98, s97
	s_or_b32 s98, s97, 0x40
	v_cmp_le_u32_e64 s[14:15], s98, v35
	s_bcnt1_i32_b64 s100, s[14:15]
	s_cmp_ge_u32 s100, 16
	s_cselect_b32 s97, s98, s97
	s_or_b32 s98, s97, 0x20
	v_cmp_le_u32_e64 s[14:15], s98, v35
	s_bcnt1_i32_b64 s100, s[14:15]
	s_cmp_ge_u32 s100, 16
	s_cselect_b32 s97, s98, s97
	s_or_b32 s98, s97, 0x10
	v_cmp_le_u32_e64 s[14:15], s98, v35
	s_bcnt1_i32_b64 s100, s[14:15]
	s_cmp_ge_u32 s100, 16
	s_cselect_b32 s97, s98, s97
	s_or_b32 s98, s97, 0x8
	v_cmp_le_u32_e64 s[14:15], s98, v35
	s_bcnt1_i32_b64 s100, s[14:15]
	s_cmp_ge_u32 s100, 16
	s_cselect_b32 s97, s98, s97
	s_or_b32 s98, s97, 0x4
	v_cmp_le_u32_e64 s[14:15], s98, v35
	s_bcnt1_i32_b64 s100, s[14:15]
	s_cmp_ge_u32 s100, 16
	s_cselect_b32 s97, s98, s97
	s_or_b32 s98, s97, 0x2
	v_cmp_le_u32_e64 s[14:15], s98, v35
	s_bcnt1_i32_b64 s100, s[14:15]
	s_cmp_ge_u32 s100, 16
	s_cselect_b32 s97, s98, s97
	s_or_b32 s98, s97, 0x1
	v_cmp_le_u32_e64 s[14:15], s98, v35
	s_bcnt1_i32_b64 s100, s[14:15]
	s_cmp_ge_u32 s100, 16
	s_cselect_b32 s97, s98, s97
	v_cmp_lt_u32_e64 s[16:17], s97, v35
	v_cmp_eq_u32_e64 s[18:19], s97, v35
	s_bcnt1_i32_b64 s100, s[16:17]
	s_sub_i32 s101, 16, s100
.Ltk_l0_tie:
	s_ff1_i32_b64 s98, s[18:19]
	s_bitset1_b64 s[16:17], s98
	s_bitset0_b64 s[18:19], s98
	s_sub_i32 s101, s101, 1
	s_cmp_lg_u32 s101, 0
	s_cbranch_scc1 .Ltk_l0_tie
	s_and_saveexec_b64 s[14:15], s[4:5]
	s_cbranch_execz .LBB0_686
	s_lshl_b32 s18, s95, 3
	s_add_i32 s18, s18, 0
	s_add_i32 s18, s18, 0x1f500
	v_mov_b32_e32 v0, s18
	v_mov_b64_e32 v[36:37], s[16:17]
	ds_write_b64 v0, v[36:37]
	s_branch .LBB0_686

; __device__ __forceinline__ void nsa_unit(int b, int qt, const bf16_t* proj, const bf16_t* vt, const bf16_t* kc, const bf16_t* vcT, bf16_t* ab0, LAS unsigned char* lds, int tid, int wid, int lane) {
;     ...
;       const bool valid = lane <= qt, forced = (lane == 0) || (lane == qt) || (lane == qt - 1);
;       float val = ((imp0[qi * 65 + lane] * linvL[qi] + imp1[qi * 65 + lane] * linvL[64 + qi]) + imp2[qi * 65 + lane] * linvL[128 + qi]) + imp3[qi * 65 + lane] * linvL[192 + qi];
;       val = valid ? (forced ? val + 1.0e4f : val) : -1.0e30f;
;       int rank = 0;
; #pragma unroll 4
;       for (int jj = 0; jj < 64; ++jj) {
;         const float o = __builtin_bit_cast(float, __builtin_amdgcn_readlane(__builtin_bit_cast(int, val), jj));
;         rank += (o > val || (o == val && jj < lane)) ? 1 : 0;
;       }
;       const unsigned long long mk = __ballot(rank < 16);
;       if (lane == 0) { selw[qi * 2] = (unsigned)mk; selw[qi * 2 + 1] = (unsigned)(mk >> 32); }
.LBB0_1526:
	s_or_b64 exec, exec, s[14:15]
	v_xor_b32_e32 v35, 0x80000000, v0
	s_mov_b32 s78, 0
	s_or_b32 s98, s78, 0x80000000
	v_cmp_le_u32_e64 s[14:15], s98, v35
	s_bcnt1_i32_b64 s100, s[14:15]
	s_cmp_ge_u32 s100, 16
	s_cselect_b32 s78, s98, s78
	s_or_b32 s98, s78, 0x40000000
	v_cmp_le_u32_e64 s[14:15], s98, v35
	s_bcnt1_i32_b64 s100, s[14:15]
	s_cmp_ge_u32 s100, 16
	s_cselect_b32 s78, s98, s78
	s_or_b32 s98, s78, 0x20000000
	v_cmp_le_u32_e64 s[14:15], s98, v35
	s_bcnt1_i32_b64 s100, s[14:15]
	s_cmp_ge_u32 s100, 16
	s_cselect_b32 s78, s98, s78
	s_or_b32 s98, s78, 0x10000000
	v_cmp_le_u32_e64 s[14:15], s98, v35
	s_bcnt1_i32_b64 s100, s[14:15]
	s_cmp_ge_u32 s100, 16
	s_cselect_b32 s78, s98, s78
	s_or_b32 s98, s78, 0x8000000
	v_cmp_le_u32_e64 s[14:15], s98, v35
	s_bcnt1_i32_b64 s100, s[14:15]
	s_cmp_ge_u32 s100, 16
	s_cselect_b32 s78, s98, s78
	s_or_b32 s98, s78, 0x4000000
	v_cmp_le_u32_e64 s[14:15], s98, v35
	s_bcnt1_i32_b64 s100, s[14:15]
	s_cmp_ge_u32 s100, 16
	s_cselect_b32 s78, s98, s78
	s_or_b32 s98, s78, 0x2000000
	v_cmp_le_u32_e64 s[14:15], s98, v35
	s_bcnt1_i32_b64 s100, s[14:15]
	s_cmp_ge_u32 s100, 16
	s_cselect_b32 s78, s98, s78
	s_or_b32 s98, s78, 0x1000000
	v_cmp_le_u32_e64 s[14:15], s98, v35
	s_bcnt1_i32_b64 s100, s[14:15]
	s_cmp_ge_u32 s100, 16
	s_cselect_b32 s78, s98, s78
	s_or_b32 s98, s78, 0x800000
	v_cmp_le_u32_e64 s[14:15], s98, v35
	s_bcnt1_i32_b64 s100, s[14:15]
	s_cmp_ge_u32 s100, 16
	s_cselect_b32 s78, s98, s78
	s_or_b32 s98, s78, 0x400000
	v_cmp_le_u32_e64 s[14:15], s98, v35
	s_bcnt1_i32_b64 s100, s[14:15]
	s_cmp_ge_u32 s100, 16
	s_cselect_b32 s78, s98, s78
	s_or_b32 s98, s78, 0x200000
	v_cmp_le_u32_e64 s[14:15], s98, v35
	s_bcnt1_i32_b64 s100, s[14:15]
	s_cmp_ge_u32 s100, 16
	s_cselect_b32 s78, s98, s78
	s_or_b32 s98, s78, 0x100000
	v_cmp_le_u32_e64 s[14:15], s98, v35
	s_bcnt1_i32_b64 s100, s[14:15]
	s_cmp_ge_u32 s100, 16
	s_cselect_b32 s78, s98, s78
	s_or_b32 s98, s78, 0x80000
	v_cmp_le_u32_e64 s[14:15], s98, v35
	s_bcnt1_i32_b64 s100, s[14:15]
	s_cmp_ge_u32 s100, 16
	s_cselect_b32 s78, s98, s78
	s_or_b32 s98, s78, 0x40000
	v_cmp_le_u32_e64 s[14:15], s98, v35
	s_bcnt1_i32_b64 s100, s[14:15]
	s_cmp_ge_u32 s100, 16
	s_cselect_b32 s78, s98, s78
	s_or_b32 s98, s78, 0x20000
	v_cmp_le_u32_e64 s[14:15], s98, v35
	s_bcnt1_i32_b64 s100, s[14:15]
	s_cmp_ge_u32 s100, 16
	s_cselect_b32 s78, s98, s78
	s_or_b32 s98, s78, 0x10000
	v_cmp_le_u32_e64 s[14:15], s98, v35
	s_bcnt1_i32_b64 s100, s[14:15]
	s_cmp_ge_u32 s100, 16
	s_cselect_b32 s78, s98, s78
	s_or_b32 s98, s78, 0x8000
	v_cmp_le_u32_e64 s[14:15], s98, v35
	s_bcnt1_i32_b64 s100, s[14:15]
	s_cmp_ge_u32 s100, 16
	s_cselect_b32 s78, s98, s78
	s_or_b32 s98, s78, 0x4000
	v_cmp_le_u32_e64 s[14:15], s98, v35
	s_bcnt1_i32_b64 s100, s[14:15]
	s_cmp_ge_u32 s100, 16
	s_cselect_b32 s78, s98, s78
	s_or_b32 s98, s78, 0x2000
	v_cmp_le_u32_e64 s[14:15], s98, v35
	s_bcnt1_i32_b64 s100, s[14:15]
	s_cmp_ge_u32 s100, 16
	s_cselect_b32 s78, s98, s78
	s_or_b32 s98, s78, 0x1000
	v_cmp_le_u32_e64 s[14:15], s98, v35
	s_bcnt1_i32_b64 s100, s[14:15]
	s_cmp_ge_u32 s100, 16
	s_cselect_b32 s78, s98, s78
	s_or_b32 s98, s78, 0x800
	v_cmp_le_u32_e64 s[14:15], s98, v35
	s_bcnt1_i32_b64 s100, s[14:15]
	s_cmp_ge_u32 s100, 16
	s_cselect_b32 s78, s98, s78
	s_or_b32 s98, s78, 0x400
	v_cmp_le_u32_e64 s[14:15], s98, v35
	s_bcnt1_i32_b64 s100, s[14:15]
	s_cmp_ge_u32 s100, 16
	s_cselect_b32 s78, s98, s78
	s_or_b32 s98, s78, 0x200
	v_cmp_le_u32_e64 s[14:15], s98, v35
	s_bcnt1_i32_b64 s100, s[14:15]
	s_cmp_ge_u32 s100, 16
	s_cselect_b32 s78, s98, s78
	s_or_b32 s98, s78, 0x100
	v_cmp_le_u32_e64 s[14:15], s98, v35
	s_bcnt1_i32_b64 s100, s[14:15]
	s_cmp_ge_u32 s100, 16
	s_cselect_b32 s78, s98, s78
	s_or_b32 s98, s78, 0x80
	v_cmp_le_u32_e64 s[14:15], s98, v35
	s_bcnt1_i32_b64 s100, s[14:15]
	s_cmp_ge_u32 s100, 16
	s_cselect_b32 s78, s98, s78
	s_or_b32 s98, s78, 0x40
	v_cmp_le_u32_e64 s[14:15], s98, v35
	s_bcnt1_i32_b64 s100, s[14:15]
	s_cmp_ge_u32 s100, 16
	s_cselect_b32 s78, s98, s78
	s_or_b32 s98, s78, 0x20
	v_cmp_le_u32_e64 s[14:15], s98, v35
	s_bcnt1_i32_b64 s100, s[14:15]
	s_cmp_ge_u32 s100, 16
	s_cselect_b32 s78, s98, s78
	s_or_b32 s98, s78, 0x10
	v_cmp_le_u32_e64 s[14:15], s98, v35
	s_bcnt1_i32_b64 s100, s[14:15]
	s_cmp_ge_u32 s100, 16
	s_cselect_b32 s78, s98, s78
	s_or_b32 s98, s78, 0x8
	v_cmp_le_u32_e64 s[14:15], s98, v35
	s_bcnt1_i32_b64 s100, s[14:15]
	s_cmp_ge_u32 s100, 16
	s_cselect_b32 s78, s98, s78
	s_or_b32 s98, s78, 0x4
	v_cmp_le_u32_e64 s[14:15], s98, v35
	s_bcnt1_i32_b64 s100, s[14:15]
	s_cmp_ge_u32 s100, 16
	s_cselect_b32 s78, s98, s78
	s_or_b32 s98, s78, 0x2
	v_cmp_le_u32_e64 s[14:15], s98, v35
	s_bcnt1_i32_b64 s100, s[14:15]
	s_cmp_ge_u32 s100, 16
	s_cselect_b32 s78, s98, s78
	s_or_b32 s98, s78, 0x1
	v_cmp_le_u32_e64 s[14:15], s98, v35
	s_bcnt1_i32_b64 s100, s[14:15]
	s_cmp_ge_u32 s100, 16
	s_cselect_b32 s78, s98, s78
	v_cmp_lt_u32_e64 s[16:17], s78, v35
	v_cmp_eq_u32_e64 s[18:19], s78, v35
	s_bcnt1_i32_b64 s100, s[16:17]
	s_sub_i32 s101, 16, s100
.Ltk_l1_tie:
	s_ff1_i32_b64 s98, s[18:19]
	s_bitset1_b64 s[16:17], s98
	s_bitset0_b64 s[18:19], s98
	s_sub_i32 s101, s101, 1
	s_cmp_lg_u32 s101, 0
	s_cbranch_scc1 .Ltk_l1_tie
	s_and_saveexec_b64 s[14:15], s[4:5]
	s_cbranch_execz .LBB0_1523
	s_lshl_b32 s18, s77, 3
	s_add_i32 s18, s18, 0
	s_add_i32 s18, s18, 0x1f500
	v_mov_b32_e32 v0, s18
	v_mov_b64_e32 v[36:37], s[16:17]
	ds_write_b64 v0, v[36:37]
	s_branch .LBB0_1523

; __global__ void __launch_bounds__(512, 2) hybrid_fwd(Args a) {
	.amdhsa_kernel _Z10hybrid_fwd4Args
		.amdhsa_group_segment_fixed_size 0
		.amdhsa_private_segment_fixed_size 0
		.amdhsa_kernarg_size 392
		.amdhsa_user_sgpr_count 2
		.amdhsa_user_sgpr_dispatch_ptr 0
		.amdhsa_user_sgpr_queue_ptr 0
		.amdhsa_user_sgpr_kernarg_segment_ptr 1
		.amdhsa_user_sgpr_dispatch_id 0
		.amdhsa_user_sgpr_kernarg_preload_length 0
		.amdhsa_user_sgpr_kernarg_preload_offset 0
		.amdhsa_user_sgpr_private_segment_size 0
		.amdhsa_uses_dynamic_stack 0
		.amdhsa_enable_private_segment 0
		.amdhsa_system_sgpr_workgroup_id_x 1
		.amdhsa_system_sgpr_workgroup_id_y 0
		.amdhsa_system_sgpr_workgroup_id_z 0
		.amdhsa_system_sgpr_workgroup_info 0
		.amdhsa_system_vgpr_workitem_id 2
		.amdhsa_next_free_vgpr 256
		.amdhsa_next_free_sgpr 102
		.amdhsa_accum_offset 256
		.amdhsa_reserve_vcc 1
		.amdhsa_float_round_mode_32 0
		.amdhsa_float_round_mode_16_64 0
		.amdhsa_float_denorm_mode_32 3
		.amdhsa_float_denorm_mode_16_64 3
		.amdhsa_dx10_clamp 1
		.amdhsa_ieee_mode 1
		.amdhsa_fp16_overflow 0
		.amdhsa_tg_split 0
		.amdhsa_exception_fp_ieee_invalid_op 0
		.amdhsa_exception_fp_denorm_src 0
		.amdhsa_exception_fp_ieee_div_zero 0
		.amdhsa_exception_fp_ieee_overflow 0
		.amdhsa_exception_fp_ieee_underflow 0
		.amdhsa_exception_fp_ieee_inexact 0
		.amdhsa_exception_int_div_zero 0
	.end_amdhsa_kernel

; __global__ void __launch_bounds__(512, 2) hybrid_fwd(Args a) {
amdhsa.kernels:
  - .agpr_count:     0
    .args:
      - .offset:         0
        .size:           136
        .value_kind:     by_value
      - .offset:         136
        .size:           4
        .value_kind:     hidden_block_count_x
      - .offset:         140
        .size:           4
        .value_kind:     hidden_block_count_y
      - .offset:         144
        .size:           4
        .value_kind:     hidden_block_count_z
      - .offset:         148
        .size:           2
        .value_kind:     hidden_group_size_x
      - .offset:         150
        .size:           2
        .value_kind:     hidden_group_size_y
      - .offset:         152
        .size:           2
        .value_kind:     hidden_group_size_z
      - .offset:         154
        .size:           2
        .value_kind:     hidden_remainder_x
      - .offset:         156
        .size:           2
        .value_kind:     hidden_remainder_y
      - .offset:         158
        .size:           2
        .value_kind:     hidden_remainder_z
      - .offset:         176
        .size:           8
        .value_kind:     hidden_global_offset_x
      - .offset:         184
        .size:           8
        .value_kind:     hidden_global_offset_y
      - .offset:         192
        .size:           8
        .value_kind:     hidden_global_offset_z
      - .offset:         200
        .size:           2
        .value_kind:     hidden_grid_dims
      - .offset:         224
        .size:           8
        .value_kind:     hidden_multigrid_sync_arg
      - .offset:         256
        .size:           4
        .value_kind:     hidden_dynamic_lds_size
    .group_segment_fixed_size: 0
    .kernarg_segment_align: 8
    .kernarg_segment_size: 392
    .language:       OpenCL C
    .language_version:
      - 2
      - 0
    .max_flat_workgroup_size: 512
    .name:           _Z10hybrid_fwd4Args
    .private_segment_fixed_size: 0
    .sgpr_count:     108
    .sgpr_spill_count: 3
    .symbol:         _Z10hybrid_fwd4Args.kd
    .uniform_work_group_size: 1
    .uses_dynamic_stack: false
    .vgpr_count:     256
    .vgpr_spill_count: 0
    .wavefront_size: 64
